# plus: unit decode division by group size (always 4) replaced by shift and mask
# baseline (speedup 1.0000x reference)
.LBB0_117:
	s_add_i32 s33, s55, 1
	s_mul_i32 s6, s33, s21
	s_mul_hi_u32 s7, s33, s22
	s_add_i32 s7, s7, s6
	s_mul_i32 s6, s33, s22
	s_add_u32 s52, s6, s2
	s_addc_u32 s53, s7, s3
	v_cmp_gt_i64_e32 vcc, s[52:53], v[152:153]
	v_cmp_lt_i64_e64 s[6:7], s[52:53], v[150:151]
	s_cbranch_vccnz .LBB0_119
	s_ashr_i32 s53, s52, 31
	s_lshr_b32 s53, s53, 29
	s_add_i32 s53, s52, s53
	s_ashr_i32 s56, s53, 3
	s_and_b32 s53, s53, -8
	s_sub_i32 s52, s52, s53
	s_cmp_lt_i32 s52, 0
	s_movk_i32 s53, 0x161
	s_cselect_b32 s53, s53, 0x160
	s_mul_i32 s52, s52, s53
	s_add_i32 s52, s52, s56
	s_mul_hi_i32 s53, s52, 0x2e8ba2e9
	s_lshr_b32 s56, s53, 31
	s_ashr_i32 s53, s53, 4
	s_add_i32 s53, s53, s56
	s_lshl_b32 s56, s53, 2
	s_sub_i32 s57, 0x80, s56
	s_min_i32 s57, s57, 4
	s_mulk_i32 s53, 0x58
	s_sub_i32 s52, s52, s53
	s_ashr_i32 s78, s52, 2
	s_and_b32 s52, s52, 3
	s_add_i32 s80, s56, s52

.LBB0_266:
	s_ashr_i32 s8, s54, 3
	s_add_i32 s8, s56, s8
	s_ashr_i32 s9, s8, 31
	s_lshr_b32 s9, s9, 28
	s_add_i32 s9, s8, s9
	s_ashr_i32 s54, s9, 4
	s_lshl_b32 s55, s54, 2
	s_sub_i32 s54, 0x80, s55
	s_min_i32 s56, s54, 4
	s_and_b32 s9, s9, -16
	s_sub_i32 s8, s8, s9
	s_ashr_i32 s54, s8, 2
	s_and_b32 s8, s8, 3
	s_add_i32 s55, s55, s8

.LBB0_426:
	s_add_i32 s79, s14, 1
	s_mul_i32 s8, s79, s56
	s_mul_hi_u32 s9, s79, s68
	s_add_i32 s9, s9, s8
	s_mul_i32 s8, s79, s68
	s_add_u32 s52, s8, s2
	s_addc_u32 s53, s9, s3
	v_cmp_gt_i64_e32 vcc, s[52:53], v[162:163]
	v_cmp_lt_i64_e64 s[8:9], s[52:53], v[160:161]
	s_cbranch_vccnz .LBB0_428
	s_ashr_i32 s15, s52, 31
	s_lshr_b32 s15, s15, 29
	s_add_i32 s15, s52, s15
	s_ashr_i32 s16, s15, 3
	s_and_b32 s15, s15, -8
	s_sub_i32 s15, s52, s15
	s_cmp_lt_i32 s15, 0
	s_movk_i32 s17, 0xa1
	s_cselect_b32 s17, s17, 0xa0
	s_mul_i32 s15, s15, s17
	s_add_i32 s15, s15, s16
	s_mul_hi_i32 s16, s15, 0x66666667
	s_lshr_b32 s17, s16, 31
	s_ashr_i32 s16, s16, 4
	s_add_i32 s16, s16, s17
	s_lshl_b32 s17, s16, 2
	s_sub_i32 s18, 0x80, s17
	s_min_i32 s18, s18, 4
	s_mul_i32 s16, s16, 40
	s_sub_i32 s15, s15, s16
	s_ashr_i32 s84, s15, 2
	s_and_b32 s15, s15, 3
	s_add_i32 s94, s17, s15

.LBB0_991:
	s_ashr_i32 s50, s52, 3
	s_add_i32 s50, s54, s50
	s_ashr_i32 s51, s50, 31
	s_lshr_b32 s51, s51, 28
	s_add_i32 s51, s50, s51
	s_ashr_i32 s52, s51, 4
	s_lshl_b32 s52, s52, 2
	s_sub_i32 s53, 0x80, s52
	s_min_i32 s53, s53, 4
	s_and_b32 s51, s51, -16
	s_sub_i32 s51, s50, s51
	s_ashr_i32 s50, s51, 2
	s_and_b32 s51, s51, 3
	s_add_i32 s52, s52, s51

.LBB0_1145:
	s_add_i32 s33, s57, 1
	s_mul_i32 s4, s33, s21
	s_mul_hi_u32 s5, s33, s22
	s_add_i32 s5, s5, s4
	s_mul_i32 s4, s33, s22
	s_add_u32 s50, s4, s2
	s_addc_u32 s51, s5, s3
	v_cmp_gt_i64_e32 vcc, s[50:51], v[144:145]
	v_cmp_lt_i64_e64 s[4:5], s[50:51], v[142:143]
	s_cbranch_vccnz .LBB0_1147
	s_ashr_i32 s46, s50, 31
	s_lshr_b32 s46, s46, 29
	s_add_i32 s46, s50, s46
	s_ashr_i32 s47, s46, 3
	s_and_b32 s46, s46, -8
	s_sub_i32 s46, s50, s46
	s_cmp_lt_i32 s46, 0
	s_movk_i32 s48, 0x161
	s_cselect_b32 s48, s48, 0x160
	s_mul_i32 s46, s46, s48
	s_add_i32 s46, s46, s47
	s_mul_hi_i32 s47, s46, 0x2e8ba2e9
	s_lshr_b32 s48, s47, 31
	s_ashr_i32 s47, s47, 4
	s_add_i32 s47, s47, s48
	s_lshl_b32 s48, s47, 2
	s_sub_i32 s49, 0x80, s48
	s_min_i32 s49, s49, 4
	s_mulk_i32 s47, 0x58
	s_sub_i32 s47, s46, s47
	s_ashr_i32 s46, s47, 2
	s_and_b32 s47, s47, 3
	s_add_i32 s48, s48, s47

.LBB0_1293:
	s_ashr_i32 s6, s52, 3
	s_add_i32 s6, s55, s6
	s_ashr_i32 s7, s6, 31
	s_lshr_b32 s7, s7, 28
	s_add_i32 s7, s6, s7
	s_ashr_i32 s52, s7, 4
	s_lshl_b32 s52, s52, 2
	s_sub_i32 s53, 0x80, s52
	s_min_i32 s53, s53, 4
	s_and_b32 s7, s7, -16
	s_sub_i32 s6, s6, s7
	s_ashr_i32 s56, s6, 2
	s_and_b32 s6, s6, 3
	s_add_i32 s57, s52, s6

.LBB0_1757:
	s_add_i32 s57, s59, 1
	s_mul_i32 s4, s57, s16
	s_mul_hi_u32 s5, s57, s22
	s_add_i32 s5, s5, s4
	s_mul_i32 s4, s57, s22
	s_add_u32 s50, s4, s2
	s_addc_u32 s51, s5, s3
	v_cmp_gt_i64_e32 vcc, s[50:51], v[158:159]
	v_cmp_lt_i64_e64 s[4:5], s[50:51], v[156:157]
	s_cbranch_vccnz .LBB0_1759
	s_ashr_i32 s46, s50, 31
	s_lshr_b32 s46, s46, 29
	s_add_i32 s46, s50, s46
	s_ashr_i32 s47, s46, 3
	s_and_b32 s46, s46, -8
	s_sub_i32 s46, s50, s46
	s_cmp_lt_i32 s46, 0
	s_movk_i32 s48, 0xc1
	s_cselect_b32 s48, s48, 0xc0
	s_mul_i32 s46, s46, s48
	s_add_i32 s46, s46, s47
	s_mul_hi_i32 s47, s46, 0x2aaaaaab
	s_lshr_b32 s48, s47, 31
	s_ashr_i32 s47, s47, 3
	s_add_i32 s47, s47, s48
	s_lshl_b32 s48, s47, 2
	s_sub_i32 s49, 0x80, s48
	s_min_i32 s49, s49, 4
	s_mul_i32 s47, s47, 48
	s_sub_i32 s47, s46, s47
	s_ashr_i32 s46, s47, 2
	s_and_b32 s47, s47, 3
	s_add_i32 s48, s48, s47

.LBB0_2189:
	s_add_i32 s55, s57, 1
	s_mul_i32 s4, s55, s21
	s_mul_hi_u32 s5, s55, s22
	s_add_i32 s5, s5, s4
	s_mul_i32 s4, s55, s22
	s_add_u32 s48, s4, s2
	s_addc_u32 s49, s5, s3
	v_cmp_gt_i64_e32 vcc, s[48:49], v[144:145]
	v_cmp_lt_i64_e64 s[4:5], s[48:49], v[142:143]
	s_cbranch_vccnz .LBB0_2191
	s_ashr_i32 s44, s48, 31
	s_lshr_b32 s44, s44, 29
	s_add_i32 s44, s48, s44
	s_ashr_i32 s45, s44, 3
	s_and_b32 s44, s44, -8
	s_sub_i32 s44, s48, s44
	s_cmp_lt_i32 s44, 0
	s_cselect_b32 s46, s25, 0x160
	s_mul_i32 s44, s44, s46
	s_add_i32 s44, s44, s45
	s_mul_hi_i32 s45, s44, 0x2e8ba2e9
	s_lshr_b32 s46, s45, 31
	s_ashr_i32 s45, s45, 4
	s_add_i32 s45, s45, s46
	s_lshl_b32 s46, s45, 2
	s_sub_i32 s47, 0x80, s46
	s_min_i32 s47, s47, 4
	s_mulk_i32 s45, 0x58
	s_sub_i32 s45, s44, s45
	s_ashr_i32 s44, s45, 2
	s_and_b32 s45, s45, 3
	s_add_i32 s46, s46, s45

.LBB0_2335:
	s_ashr_i32 s0, s14, 3
	s_add_i32 s0, s20, s0
	s_ashr_i32 s1, s0, 31
	s_lshr_b32 s1, s1, 28
	s_add_i32 s1, s0, s1
	s_ashr_i32 s14, s1, 4
	s_lshl_b32 s14, s14, 2
	s_sub_i32 s15, 0x80, s14
	s_min_i32 s15, s15, 4
	s_and_b32 s1, s1, -16
	s_sub_i32 s0, s0, s1
	s_ashr_i32 s39, s0, 2
	s_and_b32 s0, s0, 3
	s_add_i32 s40, s14, s0
